# diff-attn loop: three dead address-high v_mov (left over from the flat->ds flag conversion) and one dead s_nop removed; later code keeps its 8-byte phase
# baseline (speedup 1.0000x reference)
; DI void diff_unit(unsigned char* smem, const bf16* __restrict__ QKV, bf16* __restrict__ Y, int h, int qb, float lam, float outscale, const float* __restrict__ gain, float kn0, float kn1, int tid) {
;     ...
;     for (int it = 0;; ++it, j -= 2) {
;         const int bufo = (it & 1) * D3_BUF;
;         asm volatile("s_waitcnt vmcnt(0)" ::: "memory");
;         __syncthreads();
;         if (it > 0 && flag[(it - 1) % 3] == 0u) break;
;         if (tid == 0) flag[(it + 1) % 3] = 0u;
;         const bool mine_next = (j - 2 >= 0);
;         if (mine_next) D3_DMA(j - 2, D3_BUF - bufo);
.LBB0_204:
	s_mul_hi_u32 s10, s66, 0xaaaaaaab
	s_lshr_b32 s10, s10, 1
	s_mul_i32 s10, s10, -12
	s_add_i32 s10, s76, s10
	v_mov_b32_e32 v34, s10
	s_waitcnt vmcnt(0) lgkmcnt(0)
	s_barrier
	ds_read_b32 v34, v34
	v_add_u32_e32 v192, -2, v85
	s_waitcnt lgkmcnt(0)
	v_cmp_ne_u32_e32 vcc, 0, v34
	v_cmp_eq_u32_e64 s[10:11], 0, v34
	s_and_saveexec_b64 s[48:49], vcc
	s_cbranch_execz .LBB0_203
	s_and_saveexec_b64 s[12:13], s[6:7]
	s_cbranch_execz .LBB0_207
	s_mul_hi_u32 s14, s65, 0xaaaaaaab
	s_lshr_b32 s14, s14, 1
	s_mul_i32 s14, s14, -12
	s_add_i32 s14, s80, s14
	v_mov_b32_e32 v34, s14
	ds_write_b32 v34, v33

; DI void diff_unit(unsigned char* smem, const bf16* __restrict__ QKV, bf16* __restrict__ Y, int h, int qb, float lam, float outscale, const float* __restrict__ gain, float kn0, float kn1, int tid) {
;     ...
;         if (mine_next && !dead && lane == 0) flag[it % 3] = 1u;
;     }
.LBB0_222:
	s_or_b64 exec, exec, s[54:55]
	s_or_b64 s[12:13], s[12:13], s[16:17]
	s_nor_b64 s[14:15], s[8:9], s[12:13]
	s_and_saveexec_b64 s[12:13], s[14:15]
	s_cbranch_execz .LBB0_202
	s_mul_hi_u32 s14, s67, 0xaaaaaaab
	s_lshr_b32 s14, s14, 1
	s_mul_i32 s14, s14, -12
	s_add_i32 s14, s64, s14
	v_mov_b32_e32 v34, s14
	s_andn2_b64 s[16:17], s[16:17], exec
	ds_write_b32 v34, v202
	s_branch .LBB0_202
